# P10 epilogue x1 loads without the nt hint as well
# speedup vs baseline: 1.0030x; 1.0007x over previous
; __device__ __forceinline__ float bf2f(short s) { return __uint_as_float(((unsigned)(unsigned short)s) << 16); }
; __device__ __forceinline__ float bf2f(u16 u) { return __uint_as_float((unsigned)u << 16); }
; __device__ __forceinline__ unsigned pk2(float lo, float hi) { f32x2_t v = {lo, hi}; bf16x2_t b = __builtin_convertvector(v, bf16x2_t); return __builtin_bit_cast(unsigned, b); }
;     __device__ __forceinline__ void operator()(const pg8::f32x4 (&acc)[2][2][4][2], const pg8::Unit& u, int wr, int wc, int fr, int fq) const {
;     ...
;         for (int ai = 0; ai < 2; ++ai) {
;             pg8::f32x4 bs[4][2][2]; v4u bw[4][2];
; #pragma unroll
;             for (int m = 0; m < 4; ++m) { const size_t off = ((size_t)u.pm * 256 + ai * 128 + wr * 64 + m * 16 + fr) * DM + col0;
; #pragma unroll
;                 for (int bj = 0; bj < 2; ++bj) {
;                     if (IN_BF16) bw[m][bj] = __builtin_nontemporal_load((const v4u*)((const u16*)base + off + bj * 128));
;                     else { bs[m][bj][0] = __builtin_nontemporal_load((const pg8::f32x4*)((const float*)base + off + bj * 128)); bs[m][bj][1] = __builtin_nontemporal_load((const pg8::f32x4*)((const float*)base + off + bj * 128 + 4)); } } }
; #pragma unroll
;             for (int m = 0; m < 4; ++m) { const size_t off = ((size_t)u.pm * 256 + ai * 128 + wr * 64 + m * 16 + fr) * DM + col0;
; #pragma unroll
;                 for (int bj = 0; bj < 2; ++bj) {
;                     pg8::f32x4 b0, b1;
;                     if (IN_BF16) { const v4u w = bw[m][bj];
;                         b0 = (pg8::f32x4){bf2f((u16)(w.x & 0xffffu)), bf2f((u16)(w.x >> 16)), bf2f((u16)(w.y & 0xffffu)), bf2f((u16)(w.y >> 16))};
;                         b1 = (pg8::f32x4){bf2f((u16)(w.z & 0xffffu)), bf2f((u16)(w.z >> 16)), bf2f((u16)(w.w & 0xffffu)), bf2f((u16)(w.w >> 16))}; }
;                     else { b0 = bs[m][bj][0]; b1 = bs[m][bj][1]; }
;                     const pg8::f32x4 o0 = b0 + gv[bj][0] * acc[ai][bj][m][0], o1 = b1 + gv[bj][1] * acc[ai][bj][m][1];
;                     if (IN_BF16) { *(pg8::f32x4*)((float*)out + off + bj * 128) = o0; *(pg8::f32x4*)((float*)out + off + bj * 128 + 4) = o1; }
;                     else { v4u w; w.x = pk2(o0[0], o0[1]); w.y = pk2(o0[2], o0[3]); w.z = pk2(o1[0], o1[1]); w.w = pk2(o1[2], o1[3]); *(v4u*)((u16*)out + off + bj * 128) = w; } } }
.LBB0_911:
	v_lshl_or_b32 v128, s25, 8, v171
	s_ashr_i32 s25, s24, 31
	s_lshr_b32 s26, s25, 29
	s_add_i32 s26, s24, s26
	s_ashr_i32 s26, s26, 3
	s_mul_hi_i32 s27, s26, 0x6000
	s_mulk_i32 s26, 0x6000
	s_add_u32 s26, s38, s26
	s_addc_u32 s27, s39, s27
	s_lshl_b64 s[24:25], s[24:25], 8
	v_ashrrev_i32_e32 v129, 31, v128
	v_lshl_add_u64 v[166:167], s[24:25], 0, v[152:153]
	v_lshl_add_u64 v[164:165], v[128:129], 1, s[6:7]
	v_lshlrev_b64 v[130:131], 11, v[166:167]
	v_lshl_add_u64 v[130:131], v[164:165], 0, v[130:131]
	v_lshlrev_b64 v[162:163], 2, v[128:129]
	v_or_b32_e32 v196, 16, v166
	v_mov_b32_e32 v197, v167
	global_load_dwordx4 v[176:179], v[130:131], off
	global_load_dwordx4 v[180:183], v[130:131], off offset:256
	v_lshl_add_u64 v[132:133], s[26:27], 0, v[162:163]
	v_lshlrev_b64 v[168:169], 11, v[196:197]
	global_load_dwordx4 v[140:143], v[132:133], off
	global_load_dwordx4 v[136:139], v[132:133], off offset:16
	global_load_dwordx4 v[128:131], v[132:133], off offset:528
	s_nop 0
	global_load_dwordx4 v[132:135], v[132:133], off offset:512
	v_lshl_add_u64 v[168:169], v[164:165], 0, v[168:169]
	v_or_b32_e32 v208, 32, v166
	v_mov_b32_e32 v209, v167
	global_load_dwordx4 v[184:187], v[168:169], off
	global_load_dwordx4 v[188:191], v[168:169], off offset:256
	v_lshlrev_b64 v[168:169], 11, v[208:209]
	v_lshl_add_u64 v[198:199], v[164:165], 0, v[168:169]
	global_load_dwordx4 v[192:195], v[198:199], off
	v_or_b32_e32 v168, 48, v166
	v_mov_b32_e32 v169, v167
	v_lshlrev_b64 v[204:205], 12, v[196:197]
	global_load_dwordx4 v[196:199], v[198:199], off offset:256
	v_lshlrev_b64 v[200:201], 12, v[166:167]
	v_lshlrev_b64 v[202:203], 11, v[168:169]
	v_lshl_add_u64 v[200:201], s[12:13], 0, v[200:201]
	v_lshl_add_u64 v[206:207], v[164:165], 0, v[202:203]
	v_lshl_add_u64 v[210:211], v[200:201], 0, v[162:163]
	v_lshl_add_u64 v[212:213], s[12:13], 0, v[204:205]
	global_load_dwordx4 v[200:203], v[206:207], off
	s_nop 0
	global_load_dwordx4 v[204:207], v[206:207], off offset:256
	v_lshl_add_u64 v[212:213], v[212:213], 0, v[162:163]
	s_and_b64 vcc, exec, s[0:1]
	s_mov_b64 s[0:1], -1
	s_waitcnt vmcnt(0)
	v_and_b32_e32 v215, 0xffff0000, v176
	v_lshlrev_b32_e32 v214, 16, v176
	v_and_b32_e32 v217, 0xffff0000, v177
	v_lshlrev_b32_e32 v216, 16, v177
	v_and_b32_e32 v177, 0xffff0000, v178
	v_lshlrev_b32_e32 v176, 16, v178
	v_and_b32_e32 v219, 0xffff0000, v179
	v_lshlrev_b32_e32 v218, 16, v179
	v_and_b32_e32 v179, 0xffff0000, v180
	v_lshlrev_b32_e32 v178, 16, v180
	v_and_b32_e32 v221, 0xffff0000, v181
	v_lshlrev_b32_e32 v220, 16, v181
	v_and_b32_e32 v181, 0xffff0000, v182
	v_lshlrev_b32_e32 v180, 16, v182
	v_pk_fma_f32 v[120:121], v[120:121], v[136:137], v[176:177]
	v_pk_fma_f32 v[116:117], v[116:117], v[132:133], v[178:179]
	v_pk_fma_f32 v[112:113], v[112:113], v[128:129], v[180:181]
	v_and_b32_e32 v177, 0xffff0000, v184
	v_lshlrev_b32_e32 v176, 16, v184
	v_and_b32_e32 v179, 0xffff0000, v185
	v_lshlrev_b32_e32 v178, 16, v185
	v_and_b32_e32 v181, 0xffff0000, v186
	v_lshlrev_b32_e32 v180, 16, v186
	v_and_b32_e32 v223, 0xffff0000, v183
	v_lshlrev_b32_e32 v222, 16, v183
	v_pk_fma_f32 v[126:127], v[126:127], v[142:143], v[216:217]
	v_pk_fma_f32 v[124:125], v[124:125], v[140:141], v[214:215]
	v_and_b32_e32 v183, 0xffff0000, v187
	v_lshlrev_b32_e32 v182, 16, v187
	v_and_b32_e32 v185, 0xffff0000, v188
	v_lshlrev_b32_e32 v184, 16, v188
	v_and_b32_e32 v187, 0xffff0000, v189
	v_lshlrev_b32_e32 v186, 16, v189
	v_and_b32_e32 v189, 0xffff0000, v190
	v_pk_fma_f32 v[110:111], v[110:111], v[142:143], v[178:179]
	v_pk_fma_f32 v[108:109], v[108:109], v[140:141], v[176:177]
	v_pk_fma_f32 v[104:105], v[104:105], v[136:137], v[180:181]
	v_lshlrev_b32_e32 v188, 16, v190
	v_pk_fma_f32 v[122:123], v[122:123], v[138:139], v[218:219]
	v_pk_fma_f32 v[118:119], v[118:119], v[134:135], v[220:221]
	v_pk_fma_f32 v[114:115], v[114:115], v[130:131], v[222:223]
	global_store_dwordx4 v[210:211], v[124:127], off
	global_store_dwordx4 v[210:211], v[120:123], off offset:16
	global_store_dwordx4 v[210:211], v[116:119], off offset:512
	global_store_dwordx4 v[210:211], v[112:115], off offset:528
	v_pk_fma_f32 v[106:107], v[106:107], v[138:139], v[182:183]
	global_store_dwordx4 v[212:213], v[108:111], off
	global_store_dwordx4 v[212:213], v[104:107], off offset:16
	v_pk_fma_f32 v[102:103], v[102:103], v[134:135], v[186:187]
	v_pk_fma_f32 v[100:101], v[100:101], v[132:133], v[184:185]
	v_and_b32_e32 v105, 0xffff0000, v191
	v_lshlrev_b32_e32 v104, 16, v191
	v_pk_fma_f32 v[92:93], v[92:93], v[128:129], v[188:189]
	v_pk_fma_f32 v[94:95], v[94:95], v[130:131], v[104:105]
	global_store_dwordx4 v[212:213], v[100:103], off offset:512
	global_store_dwordx4 v[212:213], v[92:95], off offset:528
	s_nop 0
	v_and_b32_e32 v101, 0xffff0000, v194
	v_and_b32_e32 v93, 0xffff0000, v192
	v_lshlrev_b32_e32 v92, 16, v192
	v_pk_fma_f32 v[92:93], v[96:97], v[140:141], v[92:93]
	v_lshlrev_b64 v[96:97], 12, v[208:209]
	v_and_b32_e32 v95, 0xffff0000, v193
	v_lshlrev_b32_e32 v94, 16, v193
	v_lshlrev_b32_e32 v100, 16, v194
	v_and_b32_e32 v103, 0xffff0000, v195
	v_lshlrev_b32_e32 v102, 16, v195
	v_lshl_add_u64 v[96:97], s[12:13], 0, v[96:97]
	v_pk_fma_f32 v[94:95], v[98:99], v[142:143], v[94:95]
	v_pk_fma_f32 v[90:91], v[90:91], v[138:139], v[102:103]
	v_pk_fma_f32 v[88:89], v[88:89], v[136:137], v[100:101]
	v_lshl_add_u64 v[96:97], v[96:97], 0, v[162:163]
	global_store_dwordx4 v[96:97], v[92:95], off
	global_store_dwordx4 v[96:97], v[88:91], off offset:16
	v_lshl_add_u64 v[98:99], v[166:167], 0, s[16:17]
	v_and_b32_e32 v93, 0xffff0000, v198
	v_and_b32_e32 v89, 0xffff0000, v196
	v_lshlrev_b32_e32 v88, 16, v196
	v_and_b32_e32 v91, 0xffff0000, v197
; __device__ __forceinline__ float bf2f(short s) { return __uint_as_float(((unsigned)(unsigned short)s) << 16); }
; __device__ __forceinline__ float bf2f(u16 u) { return __uint_as_float((unsigned)u << 16); }
; __device__ __forceinline__ unsigned pk2(float lo, float hi) { f32x2_t v = {lo, hi}; bf16x2_t b = __builtin_convertvector(v, bf16x2_t); return __builtin_bit_cast(unsigned, b); }
;     __device__ __forceinline__ void operator()(const pg8::f32x4 (&acc)[2][2][4][2], const pg8::Unit& u, int wr, int wc, int fr, int fq) const {
;     ...
;         for (int ai = 0; ai < 2; ++ai) {
;             pg8::f32x4 bs[4][2][2]; v4u bw[4][2];
; #pragma unroll
;             for (int m = 0; m < 4; ++m) { const size_t off = ((size_t)u.pm * 256 + ai * 128 + wr * 64 + m * 16 + fr) * DM + col0;
; #pragma unroll
;                 for (int bj = 0; bj < 2; ++bj) {
;                     if (IN_BF16) bw[m][bj] = __builtin_nontemporal_load((const v4u*)((const u16*)base + off + bj * 128));
;                     else { bs[m][bj][0] = __builtin_nontemporal_load((const pg8::f32x4*)((const float*)base + off + bj * 128)); bs[m][bj][1] = __builtin_nontemporal_load((const pg8::f32x4*)((const float*)base + off + bj * 128 + 4)); } } }
; #pragma unroll
;             for (int m = 0; m < 4; ++m) { const size_t off = ((size_t)u.pm * 256 + ai * 128 + wr * 64 + m * 16 + fr) * DM + col0;
; #pragma unroll
;                 for (int bj = 0; bj < 2; ++bj) {
;                     pg8::f32x4 b0, b1;
;                     if (IN_BF16) { const v4u w = bw[m][bj];
;                         b0 = (pg8::f32x4){bf2f((u16)(w.x & 0xffffu)), bf2f((u16)(w.x >> 16)), bf2f((u16)(w.y & 0xffffu)), bf2f((u16)(w.y >> 16))};
;                         b1 = (pg8::f32x4){bf2f((u16)(w.z & 0xffffu)), bf2f((u16)(w.z >> 16)), bf2f((u16)(w.w & 0xffffu)), bf2f((u16)(w.w >> 16))}; }
;                     else { b0 = bs[m][bj][0]; b1 = bs[m][bj][1]; }
;                     const pg8::f32x4 o0 = b0 + gv[bj][0] * acc[ai][bj][m][0], o1 = b1 + gv[bj][1] * acc[ai][bj][m][1];
;                     if (IN_BF16) { *(pg8::f32x4*)((float*)out + off + bj * 128) = o0; *(pg8::f32x4*)((float*)out + off + bj * 128 + 4) = o1; }
;                     else { v4u w; w.x = pk2(o0[0], o0[1]); w.y = pk2(o0[2], o0[3]); w.z = pk2(o1[0], o1[1]); w.w = pk2(o1[2], o1[3]); *(v4u*)((u16*)out + off + bj * 128) = w; } } }
	v_lshlrev_b32_e32 v90, 16, v197
	v_lshlrev_b32_e32 v92, 16, v198
	v_and_b32_e32 v95, 0xffff0000, v199
	v_lshlrev_b32_e32 v94, 16, v199
	v_pk_fma_f32 v[86:87], v[86:87], v[134:135], v[90:91]
	v_pk_fma_f32 v[84:85], v[84:85], v[132:133], v[88:89]
	v_pk_fma_f32 v[76:77], v[76:77], v[128:129], v[92:93]
	v_pk_fma_f32 v[78:79], v[78:79], v[130:131], v[94:95]
	global_store_dwordx4 v[96:97], v[84:87], off offset:512
	global_store_dwordx4 v[96:97], v[76:79], off offset:528
	v_lshl_add_u64 v[96:97], v[166:167], 0, s[10:11]
	v_and_b32_e32 v85, 0xffff0000, v202
	v_and_b32_e32 v77, 0xffff0000, v200
	v_lshlrev_b32_e32 v76, 16, v200
	v_pk_fma_f32 v[76:77], v[80:81], v[140:141], v[76:77]
	v_lshlrev_b64 v[80:81], 12, v[168:169]
	v_and_b32_e32 v79, 0xffff0000, v201
	v_lshlrev_b32_e32 v78, 16, v201
	v_lshlrev_b32_e32 v84, 16, v202
	v_and_b32_e32 v87, 0xffff0000, v203
	v_lshlrev_b32_e32 v86, 16, v203
	v_lshl_add_u64 v[80:81], s[12:13], 0, v[80:81]
	v_pk_fma_f32 v[78:79], v[82:83], v[142:143], v[78:79]
	v_pk_fma_f32 v[74:75], v[74:75], v[138:139], v[86:87]
	v_pk_fma_f32 v[72:73], v[72:73], v[136:137], v[84:85]
	v_lshl_add_u64 v[80:81], v[80:81], 0, v[162:163]
	global_store_dwordx4 v[80:81], v[76:79], off
	global_store_dwordx4 v[80:81], v[72:75], off offset:16
	v_lshl_add_u64 v[100:101], v[166:167], 0, s[18:19]
	v_and_b32_e32 v77, 0xffff0000, v206
	v_and_b32_e32 v73, 0xffff0000, v204
	v_lshlrev_b32_e32 v72, 16, v204
	v_and_b32_e32 v75, 0xffff0000, v205
	v_lshlrev_b32_e32 v74, 16, v205
	v_lshlrev_b32_e32 v76, 16, v206
	v_and_b32_e32 v79, 0xffff0000, v207
	v_lshlrev_b32_e32 v78, 16, v207
	v_pk_fma_f32 v[70:71], v[70:71], v[134:135], v[74:75]
	v_pk_fma_f32 v[68:69], v[68:69], v[132:133], v[72:73]
	v_pk_fma_f32 v[64:65], v[64:65], v[128:129], v[76:77]
	v_pk_fma_f32 v[66:67], v[66:67], v[130:131], v[78:79]
	global_store_dwordx4 v[80:81], v[68:71], off offset:512
	global_store_dwordx4 v[80:81], v[64:67], off offset:528
	v_lshl_add_u64 v[102:103], v[166:167], 0, s[20:21]
	s_nop 0
	v_lshlrev_b64 v[64:65], 11, v[96:97]
	v_lshl_add_u64 v[64:65], v[164:165], 0, v[64:65]
	global_load_dwordx4 v[68:71], v[64:65], off
	global_load_dwordx4 v[72:75], v[64:65], off offset:256
	v_lshlrev_b64 v[64:65], 11, v[98:99]
	v_lshl_add_u64 v[64:65], v[164:165], 0, v[64:65]
	global_load_dwordx4 v[76:79], v[64:65], off
	global_load_dwordx4 v[80:83], v[64:65], off offset:256
	v_lshlrev_b64 v[64:65], 11, v[100:101]
	v_lshl_add_u64 v[64:65], v[164:165], 0, v[64:65]
	global_load_dwordx4 v[84:87], v[64:65], off
	global_load_dwordx4 v[88:91], v[64:65], off offset:256
	v_lshlrev_b64 v[64:65], 11, v[102:103]
	v_lshl_add_u64 v[64:65], v[164:165], 0, v[64:65]
	global_load_dwordx4 v[92:95], v[64:65], off
	s_nop 0
	global_load_dwordx4 v[64:67], v[64:65], off offset:256
	s_waitcnt vmcnt(7)
	v_and_b32_e32 v105, 0xffff0000, v68
	v_lshlrev_b32_e32 v104, 16, v68
	v_and_b32_e32 v107, 0xffff0000, v69
	v_lshlrev_b32_e32 v106, 16, v69
	v_and_b32_e32 v69, 0xffff0000, v70
	v_lshlrev_b32_e32 v68, 16, v70
	v_pk_fma_f32 v[56:57], v[56:57], v[136:137], v[68:69]
	v_lshlrev_b64 v[68:69], 12, v[96:97]
	v_and_b32_e32 v109, 0xffff0000, v71
	v_lshlrev_b32_e32 v108, 16, v71
	v_lshl_add_u64 v[68:69], s[12:13], 0, v[68:69]
	v_pk_fma_f32 v[62:63], v[62:63], v[142:143], v[106:107]
	v_pk_fma_f32 v[60:61], v[60:61], v[140:141], v[104:105]
	v_pk_fma_f32 v[58:59], v[58:59], v[138:139], v[108:109]
	v_lshl_add_u64 v[68:69], v[68:69], 0, v[162:163]
	global_store_dwordx4 v[68:69], v[60:63], off
	global_store_dwordx4 v[68:69], v[56:59], off offset:16
	s_waitcnt vmcnt(8)
	v_and_b32_e32 v61, 0xffff0000, v74
	v_and_b32_e32 v57, 0xffff0000, v72
	v_lshlrev_b32_e32 v56, 16, v72
	v_and_b32_e32 v59, 0xffff0000, v73
	v_lshlrev_b32_e32 v58, 16, v73
	v_lshlrev_b32_e32 v60, 16, v74
	v_and_b32_e32 v63, 0xffff0000, v75
	v_lshlrev_b32_e32 v62, 16, v75
	v_pk_fma_f32 v[54:55], v[54:55], v[134:135], v[58:59]
	v_pk_fma_f32 v[52:53], v[52:53], v[132:133], v[56:57]
	v_pk_fma_f32 v[44:45], v[44:45], v[128:129], v[60:61]
	v_pk_fma_f32 v[46:47], v[46:47], v[130:131], v[62:63]
	global_store_dwordx4 v[68:69], v[52:55], off offset:512
	global_store_dwordx4 v[68:69], v[44:47], off offset:528
	s_waitcnt vmcnt(9)
; __device__ __forceinline__ float bf2f(short s) { return __uint_as_float(((unsigned)(unsigned short)s) << 16); }
; __device__ __forceinline__ float bf2f(u16 u) { return __uint_as_float((unsigned)u << 16); }
; __device__ __forceinline__ unsigned pk2(float lo, float hi) { f32x2_t v = {lo, hi}; bf16x2_t b = __builtin_convertvector(v, bf16x2_t); return __builtin_bit_cast(unsigned, b); }
;     __device__ __forceinline__ void operator()(const pg8::f32x4 (&acc)[2][2][4][2], const pg8::Unit& u, int wr, int wc, int fr, int fq) const {
;     ...
;             for (int m = 0; m < 4; ++m) { const size_t off = ((size_t)u.pm * 256 + ai * 128 + wr * 64 + m * 16 + fr) * DM + col0;
; #pragma unroll
;                 for (int bj = 0; bj < 2; ++bj) {
;                     pg8::f32x4 b0, b1;
;                     if (IN_BF16) { const v4u w = bw[m][bj];
;                         b0 = (pg8::f32x4){bf2f((u16)(w.x & 0xffffu)), bf2f((u16)(w.x >> 16)), bf2f((u16)(w.y & 0xffffu)), bf2f((u16)(w.y >> 16))};
;                         b1 = (pg8::f32x4){bf2f((u16)(w.z & 0xffffu)), bf2f((u16)(w.z >> 16)), bf2f((u16)(w.w & 0xffffu)), bf2f((u16)(w.w >> 16))}; }
;                     else { b0 = bs[m][bj][0]; b1 = bs[m][bj][1]; }
;                     const pg8::f32x4 o0 = b0 + gv[bj][0] * acc[ai][bj][m][0], o1 = b1 + gv[bj][1] * acc[ai][bj][m][1];
;                     if (IN_BF16) { *(pg8::f32x4*)((float*)out + off + bj * 128) = o0; *(pg8::f32x4*)((float*)out + off + bj * 128 + 4) = o1; }
;                     else { v4u w; w.x = pk2(o0[0], o0[1]); w.y = pk2(o0[2], o0[3]); w.z = pk2(o1[0], o1[1]); w.w = pk2(o1[2], o1[3]); *(v4u*)((u16*)out + off + bj * 128) = w; } } }
	v_and_b32_e32 v53, 0xffff0000, v78
	v_and_b32_e32 v45, 0xffff0000, v76
	v_lshlrev_b32_e32 v44, 16, v76
	v_pk_fma_f32 v[44:45], v[48:49], v[140:141], v[44:45]
	v_lshlrev_b64 v[48:49], 12, v[98:99]
	v_and_b32_e32 v47, 0xffff0000, v77
	v_lshlrev_b32_e32 v46, 16, v77
	v_lshlrev_b32_e32 v52, 16, v78
	v_and_b32_e32 v55, 0xffff0000, v79
	v_lshlrev_b32_e32 v54, 16, v79
	v_lshl_add_u64 v[48:49], s[12:13], 0, v[48:49]
	v_pk_fma_f32 v[46:47], v[50:51], v[142:143], v[46:47]
	v_pk_fma_f32 v[42:43], v[42:43], v[138:139], v[54:55]
	v_pk_fma_f32 v[40:41], v[40:41], v[136:137], v[52:53]
	v_lshl_add_u64 v[48:49], v[48:49], 0, v[162:163]
	global_store_dwordx4 v[48:49], v[44:47], off
	global_store_dwordx4 v[48:49], v[40:43], off offset:16
	s_waitcnt vmcnt(10)
	v_and_b32_e32 v45, 0xffff0000, v82
	v_and_b32_e32 v41, 0xffff0000, v80
	v_lshlrev_b32_e32 v40, 16, v80
	v_and_b32_e32 v43, 0xffff0000, v81
	v_lshlrev_b32_e32 v42, 16, v81
	v_lshlrev_b32_e32 v44, 16, v82
	v_and_b32_e32 v47, 0xffff0000, v83
	v_lshlrev_b32_e32 v46, 16, v83
	v_pk_fma_f32 v[38:39], v[38:39], v[134:135], v[42:43]
	v_pk_fma_f32 v[36:37], v[36:37], v[132:133], v[40:41]
	v_pk_fma_f32 v[28:29], v[28:29], v[128:129], v[44:45]
	v_pk_fma_f32 v[30:31], v[30:31], v[130:131], v[46:47]
	global_store_dwordx4 v[48:49], v[36:39], off offset:512
	global_store_dwordx4 v[48:49], v[28:31], off offset:528
	s_waitcnt vmcnt(11)
	v_and_b32_e32 v37, 0xffff0000, v86
	v_and_b32_e32 v29, 0xffff0000, v84
	v_lshlrev_b32_e32 v28, 16, v84
	v_pk_fma_f32 v[28:29], v[32:33], v[140:141], v[28:29]
	v_lshlrev_b64 v[32:33], 12, v[100:101]
	v_and_b32_e32 v31, 0xffff0000, v85
	v_lshlrev_b32_e32 v30, 16, v85
	v_lshlrev_b32_e32 v36, 16, v86
	v_and_b32_e32 v39, 0xffff0000, v87
	v_lshlrev_b32_e32 v38, 16, v87
	v_lshl_add_u64 v[32:33], s[12:13], 0, v[32:33]
	v_pk_fma_f32 v[30:31], v[34:35], v[142:143], v[30:31]
	v_pk_fma_f32 v[26:27], v[26:27], v[138:139], v[38:39]
	v_pk_fma_f32 v[24:25], v[24:25], v[136:137], v[36:37]
	v_lshl_add_u64 v[32:33], v[32:33], 0, v[162:163]
	global_store_dwordx4 v[32:33], v[28:31], off
	global_store_dwordx4 v[32:33], v[24:27], off offset:16
	s_waitcnt vmcnt(12)
	v_and_b32_e32 v29, 0xffff0000, v90
	v_and_b32_e32 v25, 0xffff0000, v88
	v_lshlrev_b32_e32 v24, 16, v88
	v_and_b32_e32 v27, 0xffff0000, v89
	v_lshlrev_b32_e32 v26, 16, v89
	v_lshlrev_b32_e32 v28, 16, v90
	v_and_b32_e32 v31, 0xffff0000, v91
	v_lshlrev_b32_e32 v30, 16, v91
	v_pk_fma_f32 v[22:23], v[22:23], v[134:135], v[26:27]
	v_pk_fma_f32 v[20:21], v[20:21], v[132:133], v[24:25]
	v_pk_fma_f32 v[12:13], v[12:13], v[128:129], v[28:29]
	v_pk_fma_f32 v[14:15], v[14:15], v[130:131], v[30:31]
	global_store_dwordx4 v[32:33], v[20:23], off offset:512
	global_store_dwordx4 v[32:33], v[12:15], off offset:528
	s_waitcnt vmcnt(13)
	v_and_b32_e32 v21, 0xffff0000, v94
	v_and_b32_e32 v13, 0xffff0000, v92
	v_lshlrev_b32_e32 v12, 16, v92
	v_pk_fma_f32 v[12:13], v[16:17], v[140:141], v[12:13]
	v_lshlrev_b64 v[16:17], 12, v[102:103]
	v_and_b32_e32 v15, 0xffff0000, v93
	v_lshlrev_b32_e32 v14, 16, v93
	v_lshlrev_b32_e32 v20, 16, v94
	v_and_b32_e32 v23, 0xffff0000, v95
	v_lshlrev_b32_e32 v22, 16, v95
	v_lshl_add_u64 v[16:17], s[12:13], 0, v[16:17]
	v_pk_fma_f32 v[14:15], v[18:19], v[142:143], v[14:15]
	v_pk_fma_f32 v[10:11], v[10:11], v[138:139], v[22:23]
	v_pk_fma_f32 v[8:9], v[8:9], v[136:137], v[20:21]
	v_lshl_add_u64 v[16:17], v[16:17], 0, v[162:163]
	global_store_dwordx4 v[16:17], v[12:15], off
	global_store_dwordx4 v[16:17], v[8:11], off offset:16
	s_waitcnt vmcnt(14)
	v_and_b32_e32 v13, 0xffff0000, v66
	v_and_b32_e32 v9, 0xffff0000, v64
	v_lshlrev_b32_e32 v8, 16, v64
	v_and_b32_e32 v11, 0xffff0000, v65
	v_lshlrev_b32_e32 v10, 16, v65
	v_lshlrev_b32_e32 v12, 16, v66
	v_and_b32_e32 v15, 0xffff0000, v67
	v_lshlrev_b32_e32 v14, 16, v67
	v_pk_fma_f32 v[6:7], v[6:7], v[134:135], v[10:11]
	v_pk_fma_f32 v[4:5], v[4:5], v[132:133], v[8:9]
	v_pk_fma_f32 v[2:3], v[2:3], v[130:131], v[14:15]
	v_pk_fma_f32 v[0:1], v[0:1], v[128:129], v[12:13]
	global_store_dwordx4 v[16:17], v[4:7], off offset:512
	global_store_dwordx4 v[16:17], v[0:3], off offset:528
	s_cbranch_vccnz .LBB0_896
	s_andn2_b64 vcc, exec, s[4:5]
	s_cbranch_vccnz .LBB0_895
	s_barrier
	s_branch .LBB0_895
